# ssm_b recurrence as two-level FMA chains on preloaded B*u values (6 instructions per step instead of pk_mul/pk_fma/mov/pk_add + nops)
# baseline (speedup 1.0000x reference)
.LBB0_230:
	s_waitcnt lgkmcnt(0)
	v_mfma_f32_16x16x16_bf16 v[50:53], v[46:47], v[10:11], 0
	v_add_u32_e32 v49, 0x4000, v119
	v_add_u32_e32 v97, 0x4800, v119
	s_and_b64 vcc, exec, s[38:39]
	v_mfma_f32_16x16x16_bf16 v[126:129], v[46:47], v[18:19], 0
	v_mfma_f32_16x16x16_bf16 v[130:133], v[46:47], v[12:13], 0
	s_nop 2
	v_mov_b32_e32 v108, v50
	s_nop 2
	v_mov_b32_e32 v109, v126
	v_mov_b32_e32 v126, v51
	v_mov_b32_e32 v138, v52
	v_mov_b32_e32 v139, v128
	v_mov_b32_e32 v128, v53
	v_mfma_f32_16x16x16_bf16 v[50:53], v[46:47], v[20:21], 0
	v_mov_b32_e32 v134, v130
	s_nop 6
	v_mov_b32_e32 v135, v50
	v_mov_b32_e32 v50, v131
	ds_write2_b64 v49, v[126:127], v[50:51] offset0:194 offset1:210
	v_mov_b32_e32 v50, v132
	v_mov_b32_e32 v51, v52
	v_mov_b32_e32 v52, v133
	ds_write2_b64 v49, v[108:109], v[134:135] offset0:128 offset1:144
	v_mfma_f32_16x16x16_bf16 v[134:137], v[46:47], v[14:15], 0
	ds_write2_b64 v97, v[138:139], v[50:51] offset0:4 offset1:20
	ds_write2_b64 v97, v[128:129], v[52:53] offset0:70 offset1:86
	v_mfma_f32_16x16x16_bf16 v[130:133], v[46:47], v[22:23], 0
	v_mfma_f32_16x16x16_bf16 v[50:53], v[46:47], v[16:17], 0
	s_nop 3
	v_mov_b32_e32 v108, v134
	s_nop 1
	v_mov_b32_e32 v109, v130
	v_mov_b32_e32 v130, v135
	v_mfma_f32_16x16x16_bf16 v[126:129], v[46:47], v[24:25], 0
	v_mov_b32_e32 v134, v136
	v_mov_b32_e32 v46, v50
	v_mov_b32_e32 v135, v132
	v_mov_b32_e32 v132, v137
	s_nop 3
	v_mov_b32_e32 v47, v126
	ds_write2_b64 v49, v[108:109], v[46:47] offset0:160 offset1:176
	v_mov_b32_e32 v126, v51
	v_mov_b32_e32 v46, v52
	v_mov_b32_e32 v47, v128
	v_mov_b32_e32 v128, v53
	ds_write2_b64 v49, v[130:131], v[126:127] offset0:226 offset1:242
	ds_write2_b64 v97, v[134:135], v[46:47] offset0:36 offset1:52
	ds_write2_b64 v97, v[132:133], v[128:129] offset0:102 offset1:118
	s_waitcnt lgkmcnt(0)
	ds_read_b64 v[206:207], v114 offset:17408
	ds_read_b64 v[208:209], v114 offset:17936
	ds_read_b64 v[210:211], v114 offset:18464
	ds_read_b64 v[212:213], v114 offset:18992
	ds_read_b64 v[214:215], v114 offset:19520
	ds_read_b64 v[216:217], v114 offset:20048
	ds_read_b64 v[218:219], v114 offset:20576
	ds_read_b64 v[220:221], v114 offset:21104
	ds_read_b64 v[222:223], v114 offset:21632
	ds_read_b64 v[224:225], v114 offset:22160
	ds_read_b64 v[226:227], v114 offset:22688
	ds_read_b64 v[228:229], v114 offset:23216
	ds_read_b64 v[230:231], v114 offset:23744
	ds_read_b64 v[232:233], v114 offset:24272
	ds_read_b64 v[234:235], v114 offset:24800
	s_waitcnt lgkmcnt(7)
	ds_read_b64 v[236:237], v114 offset:25328
	v_fma_f32 v50, v78, v0, v206
	v_fma_f32 v51, v78, v48, v207
	v_fma_f32 v52, -v96, v48, v50
	v_fma_f32 v53, v96, v0, v51
	v_cvt_pk_bf16_f32 v0, v52, v53
	ds_write_b32 v121, v0 offset:25856
	v_fma_f32 v50, v78, v52, v208
	v_fma_f32 v51, v78, v53, v209
	v_fma_f32 v46, -v96, v53, v50
	v_fma_f32 v47, v96, v52, v51
	v_cvt_pk_bf16_f32 v0, v46, v47
	ds_write_b32 v121, v0 offset:26128
	v_fma_f32 v50, v78, v46, v210
	v_fma_f32 v51, v78, v47, v211
	v_fma_f32 v52, -v96, v47, v50
	v_fma_f32 v53, v96, v46, v51
	v_cvt_pk_bf16_f32 v0, v52, v53
	ds_write_b32 v121, v0 offset:26400
	v_fma_f32 v50, v78, v52, v212
	v_fma_f32 v51, v78, v53, v213
	v_fma_f32 v46, -v96, v53, v50
	v_fma_f32 v47, v96, v52, v51
	v_cvt_pk_bf16_f32 v0, v46, v47
	ds_write_b32 v121, v0 offset:26672
	s_cbranch_vccnz .LBB0_232
	s_load_dwordx2 s[2:3], s[80:81], 0xf0
	v_lshlrev_b32_e32 v0, 2, v54
	s_waitcnt lgkmcnt(0)
	s_add_u32 s2, s2, s0
	s_addc_u32 s3, s3, s1
	s_add_u32 s2, s2, s34
	s_addc_u32 s3, s3, s35
	s_add_u32 s2, s2, s40
	s_addc_u32 s3, s3, s41
	v_lshl_add_u64 v[48:49], s[2:3], 0, v[0:1]
	v_add_co_u32_e32 v50, vcc, 0x4260000, v48
	s_nop 1
	v_addc_co_u32_e32 v51, vcc, 0, v49, vcc
	v_add_co_u32_e32 v48, vcc, 0x4660000, v48
	global_store_dword v[50:51], v46, off
	s_nop 0
	v_addc_co_u32_e32 v49, vcc, 0, v49, vcc
	global_store_dword v[48:49], v47, off
	v_mov_b64_e32 v[46:47], v[72:73]
.LBB0_232:
	v_fma_f32 v50, v78, v46, v214
	v_fma_f32 v51, v78, v47, v215
	s_and_b64 vcc, exec, s[38:39]
	v_fma_f32 v52, -v96, v47, v50
	v_fma_f32 v53, v96, v46, v51
	v_cvt_pk_bf16_f32 v0, v52, v53
	ds_write_b32 v121, v0 offset:26944
	v_fma_f32 v50, v78, v52, v216
	v_fma_f32 v51, v78, v53, v217
	v_fma_f32 v46, -v96, v53, v50
	v_fma_f32 v47, v96, v52, v51
	v_cvt_pk_bf16_f32 v0, v46, v47
	ds_write_b32 v121, v0 offset:27216
	v_fma_f32 v50, v78, v46, v218
	v_fma_f32 v51, v78, v47, v219
	v_fma_f32 v52, -v96, v47, v50
	v_fma_f32 v53, v96, v46, v51
	v_cvt_pk_bf16_f32 v0, v52, v53
	ds_write_b32 v121, v0 offset:27488
	v_fma_f32 v50, v78, v52, v220
	v_fma_f32 v51, v78, v53, v221
	v_fma_f32 v46, -v96, v53, v50
	v_fma_f32 v47, v96, v52, v51
	v_cvt_pk_bf16_f32 v0, v46, v47
	ds_write_b32 v121, v0 offset:27760
	s_cbranch_vccnz .LBB0_234
	s_load_dwordx2 s[2:3], s[80:81], 0xf0
	v_lshlrev_b32_e32 v0, 2, v54
	s_waitcnt lgkmcnt(0)
	s_add_u32 s2, s2, s42
	s_addc_u32 s3, s3, s43
	s_add_u32 s2, s2, s34
	s_addc_u32 s3, s3, s35
	s_add_u32 s2, s2, s40
	s_addc_u32 s3, s3, s41
	v_lshl_add_u64 v[48:49], s[2:3], 0, v[0:1]
	v_add_co_u32_e32 v50, vcc, 0x4260000, v48
	s_nop 1
	v_addc_co_u32_e32 v51, vcc, 0, v49, vcc
	v_add_co_u32_e32 v48, vcc, 0x4660000, v48
	global_store_dword v[50:51], v46, off
	s_nop 0
	v_addc_co_u32_e32 v49, vcc, 0, v49, vcc
	global_store_dword v[48:49], v47, off
	v_mov_b64_e32 v[46:47], v[74:75]
.LBB0_234:
	s_waitcnt lgkmcnt(8)
	v_fma_f32 v50, v78, v46, v222
	v_fma_f32 v51, v78, v47, v223
	s_and_b64 vcc, exec, s[38:39]
	v_fma_f32 v52, -v96, v47, v50
	v_fma_f32 v53, v96, v46, v51
	v_cvt_pk_bf16_f32 v0, v52, v53
	ds_write_b32 v121, v0 offset:28032
	v_fma_f32 v50, v78, v52, v224
	v_fma_f32 v51, v78, v53, v225
	v_fma_f32 v46, -v96, v53, v50
	v_fma_f32 v47, v96, v52, v51
	v_cvt_pk_bf16_f32 v0, v46, v47
	ds_write_b32 v121, v0 offset:28304
	v_fma_f32 v50, v78, v46, v226
	v_fma_f32 v51, v78, v47, v227
	v_fma_f32 v52, -v96, v47, v50
	v_fma_f32 v53, v96, v46, v51
	v_cvt_pk_bf16_f32 v0, v52, v53
	ds_write_b32 v121, v0 offset:28576
	v_fma_f32 v50, v78, v52, v228
	v_fma_f32 v51, v78, v53, v229
	v_fma_f32 v46, -v96, v53, v50
	v_fma_f32 v47, v96, v52, v51
	v_cvt_pk_bf16_f32 v0, v46, v47
	ds_write_b32 v121, v0 offset:28848
	s_cbranch_vccnz .LBB0_236
	s_load_dwordx2 s[2:3], s[80:81], 0xf0
	v_lshlrev_b32_e32 v0, 2, v54
	s_waitcnt lgkmcnt(0)
	s_add_u32 s2, s2, s44
	s_addc_u32 s3, s3, s45
	s_add_u32 s2, s2, s34
	s_addc_u32 s3, s3, s35
	s_add_u32 s2, s2, s40
	s_addc_u32 s3, s3, s41
	v_lshl_add_u64 v[48:49], s[2:3], 0, v[0:1]
	v_add_co_u32_e32 v50, vcc, 0x4260000, v48
	s_nop 1
	v_addc_co_u32_e32 v51, vcc, 0, v49, vcc
	v_add_co_u32_e32 v48, vcc, 0x4660000, v48
	global_store_dword v[50:51], v46, off
	s_nop 0
	v_addc_co_u32_e32 v49, vcc, 0, v49, vcc
	global_store_dword v[48:49], v47, off
	v_mov_b64_e32 v[46:47], v[76:77]
.LBB0_236:
	v_fma_f32 v50, v78, v46, v230
	v_fma_f32 v51, v78, v47, v231
	v_fma_f32 v52, -v96, v47, v50
	v_fma_f32 v53, v96, v46, v51
	v_cvt_pk_bf16_f32 v0, v52, v53
	ds_write_b32 v121, v0 offset:29120
	v_fma_f32 v50, v78, v52, v232
	v_fma_f32 v51, v78, v53, v233
	v_fma_f32 v46, -v96, v53, v50
	v_fma_f32 v47, v96, v52, v51
	v_cvt_pk_bf16_f32 v0, v46, v47
	ds_write_b32 v121, v0 offset:29392
	v_fma_f32 v50, v78, v46, v234
	v_fma_f32 v51, v78, v47, v235
	s_and_b64 vcc, exec, s[38:39]
	v_fma_f32 v52, -v96, v47, v50
	v_fma_f32 v53, v96, v46, v51
	v_cvt_pk_bf16_f32 v0, v52, v53
	ds_write_b32 v121, v0 offset:29664
	v_fma_f32 v50, v78, v52, v236
	v_fma_f32 v51, v78, v53, v237
	v_fma_f32 v97, -v96, v53, v50
	v_fma_f32 v124, v96, v52, v51
	v_cvt_pk_bf16_f32 v0, v97, v124
	ds_write_b32 v121, v0 offset:29936
	s_cbranch_vccnz .LBB0_238
	s_load_dwordx2 s[2:3], s[80:81], 0xf0
	v_lshlrev_b32_e32 v0, 2, v54
	s_waitcnt lgkmcnt(0)
	s_add_u32 s2, s2, s46
	s_addc_u32 s3, s3, s47
	s_add_u32 s2, s2, s34
	s_addc_u32 s3, s3, s35
	s_add_u32 s2, s2, s40
	s_addc_u32 s3, s3, s41
	v_lshl_add_u64 v[46:47], s[2:3], 0, v[0:1]
	v_add_co_u32_e32 v48, vcc, 0x4260000, v46
	s_nop 1
	v_addc_co_u32_e32 v49, vcc, 0, v47, vcc
	v_add_co_u32_e32 v46, vcc, 0x4660000, v46
	global_store_dword v[48:49], v97, off
	s_nop 0
	v_addc_co_u32_e32 v47, vcc, 0, v47, vcc
	global_store_dword v[46:47], v124, off
